# SSD scan pass: state-update LDS reads software-pipelined two k-steps ahead (extra regs v220-v247), on top of DPP scans
# baseline (speedup 1.0000x reference)
; __device__ __forceinline__ unsigned pack2(float a, float b) { const f32v2_t v = {a, b}; return __builtin_bit_cast(unsigned, __builtin_convertvector(v, bf16v2_t)); }
; __device__ __forceinline__ f32x4 mfma16(bf16x8 a, bf16x8 b, f32x4 c) { return __builtin_amdgcn_mfma_f32_16x16x32_bf16(a, b, c, 0, 0, 0); }
; __device__ __forceinline__ void ssd_scan_item(CParams& p, int j2, int b, int dir, int h, int pq, bf16_t* smem) {
;     ...
;         {
;             const float dec = sdec[0];
;             st[0] *= dec; st[1] *= dec;
; #pragma unroll
;             for (int ks = 0; ks < 4; ++ks) {
;                 const f32x4 w0 = *(const f32x4*)(sw + ks * 32 + quad * 8), w1 = *(const f32x4*)(sw + ks * 32 + quad * 8 + 4);
;                 const u32x4 raw = *(const u32x4*)(sX + l16 * SST + ks * 32 + quad * 8);
;                 u32x4 xs;
;                 xs.x = pack2(__uint_as_float(raw.x << 16) * w0[0], __uint_as_float(raw.x & 0xffff0000u) * w0[1]);
;                 xs.y = pack2(__uint_as_float(raw.y << 16) * w0[2], __uint_as_float(raw.y & 0xffff0000u) * w0[3]);
;                 xs.z = pack2(__uint_as_float(raw.z << 16) * w1[0], __uint_as_float(raw.z & 0xffff0000u) * w1[1]);
;                 xs.w = pack2(__uint_as_float(raw.w << 16) * w1[2], __uint_as_float(raw.w & 0xffff0000u) * w1[3]);
;                 const bf16x8 xbf = __builtin_bit_cast(bf16x8, xs);
; #pragma unroll
;                 for (int nt = 0; nt < 2; ++nt) st[nt] = mfma16(__builtin_bit_cast(bf16x8, S.bt[nt][ks]), xbf, st[nt]);
;             }
.LBB0_461:
	ds_read_b32 v246, v165 offset:9728
	ds_read_b128 v[176:179], v172 offset:9216
	ds_read_b128 v[180:183], v172 offset:9232
	ds_read_b128 v[184:187], v170
	ds_read_b128 v[220:223], v172 offset:9344
	ds_read_b128 v[224:227], v172 offset:9360
	ds_read_b128 v[228:231], v170 offset:64
	s_waitcnt lgkmcnt(6)
	v_pk_mul_f32 v[142:143], v[142:143], v[246:247] op_sel_hi:[1,0]
	v_pk_mul_f32 v[140:141], v[140:141], v[246:247] op_sel_hi:[1,0]
	v_pk_mul_f32 v[138:139], v[138:139], v[246:247] op_sel_hi:[1,0]
	v_pk_mul_f32 v[136:137], v[136:137], v[246:247] op_sel_hi:[1,0]
	s_waitcnt lgkmcnt(3)
	v_lshlrev_b32_e32 v188, 16, v184
	v_and_b32_e32 v189, 0xffff0000, v184
	v_pk_mul_f32 v[176:177], v[176:177], v[188:189]
	v_lshlrev_b32_e32 v188, 16, v185
	v_and_b32_e32 v189, 0xffff0000, v185
	v_pk_mul_f32 v[178:179], v[178:179], v[188:189]
	v_lshlrev_b32_e32 v188, 16, v186
	v_and_b32_e32 v189, 0xffff0000, v186
	v_pk_mul_f32 v[180:181], v[180:181], v[188:189]
	v_lshlrev_b32_e32 v188, 16, v187
	v_and_b32_e32 v189, 0xffff0000, v187
	v_pk_mul_f32 v[182:183], v[182:183], v[188:189]
	v_cvt_pk_bf16_f32 v176, v176, v177
	v_cvt_pk_bf16_f32 v177, v178, v179
	v_cvt_pk_bf16_f32 v178, v180, v181
	v_cvt_pk_bf16_f32 v179, v182, v183
	ds_read_b128 v[232:235], v172 offset:9472
	ds_read_b128 v[236:239], v172 offset:9488
	ds_read_b128 v[240:243], v170 offset:128
	s_waitcnt vmcnt(41)
	s_nop 1
	v_mfma_f32_16x16x32_bf16 v[128:131], v[128:131], v[176:179], v[140:143]
	s_waitcnt vmcnt(37)
	v_mfma_f32_16x16x32_bf16 v[132:135], v[132:135], v[176:179], v[136:139]
	s_waitcnt lgkmcnt(3)
	v_lshlrev_b32_e32 v244, 16, v228
	v_and_b32_e32 v245, 0xffff0000, v228
	v_pk_mul_f32 v[220:221], v[220:221], v[244:245]
	v_lshlrev_b32_e32 v244, 16, v229
	v_and_b32_e32 v245, 0xffff0000, v229
	v_pk_mul_f32 v[222:223], v[222:223], v[244:245]
	v_lshlrev_b32_e32 v244, 16, v230
	v_and_b32_e32 v245, 0xffff0000, v230
	v_pk_mul_f32 v[224:225], v[224:225], v[244:245]
	v_lshlrev_b32_e32 v244, 16, v231
	v_and_b32_e32 v245, 0xffff0000, v231
	v_pk_mul_f32 v[226:227], v[226:227], v[244:245]
	v_cvt_pk_bf16_f32 v220, v220, v221
	v_cvt_pk_bf16_f32 v221, v222, v223
	v_cvt_pk_bf16_f32 v222, v224, v225
	v_cvt_pk_bf16_f32 v223, v226, v227
	ds_read_b128 v[176:179], v172 offset:9600
	ds_read_b128 v[180:183], v172 offset:9616
	ds_read_b128 v[184:187], v170 offset:192
	s_nop 1
	v_mfma_f32_16x16x32_bf16 v[120:123], v[120:123], v[220:223], v[128:131]
	s_waitcnt vmcnt(36)
	v_mfma_f32_16x16x32_bf16 v[124:127], v[124:127], v[220:223], v[132:135]
	s_waitcnt lgkmcnt(3)
	v_lshlrev_b32_e32 v244, 16, v240
	v_and_b32_e32 v245, 0xffff0000, v240
	v_pk_mul_f32 v[232:233], v[232:233], v[244:245]
	v_lshlrev_b32_e32 v244, 16, v241
	v_and_b32_e32 v245, 0xffff0000, v241
	v_pk_mul_f32 v[234:235], v[234:235], v[244:245]
	v_lshlrev_b32_e32 v244, 16, v242
	v_and_b32_e32 v245, 0xffff0000, v242
	v_pk_mul_f32 v[236:237], v[236:237], v[244:245]
	v_lshlrev_b32_e32 v244, 16, v243
	v_and_b32_e32 v245, 0xffff0000, v243
	v_pk_mul_f32 v[238:239], v[238:239], v[244:245]
	v_cvt_pk_bf16_f32 v232, v232, v233
	v_cvt_pk_bf16_f32 v233, v234, v235
	v_cvt_pk_bf16_f32 v234, v236, v237
	v_cvt_pk_bf16_f32 v235, v238, v239
	s_nop 1
	v_mfma_f32_16x16x32_bf16 v[112:115], v[112:115], v[232:235], v[120:123]
	s_waitcnt vmcnt(35)
	v_mfma_f32_16x16x32_bf16 v[116:119], v[116:119], v[232:235], v[124:127]
	s_waitcnt lgkmcnt(0)
	v_lshlrev_b32_e32 v188, 16, v184
	v_and_b32_e32 v189, 0xffff0000, v184
	v_pk_mul_f32 v[176:177], v[176:177], v[188:189]
	v_lshlrev_b32_e32 v188, 16, v185
	v_and_b32_e32 v189, 0xffff0000, v185
	v_pk_mul_f32 v[178:179], v[178:179], v[188:189]
	v_lshlrev_b32_e32 v188, 16, v186
	v_and_b32_e32 v189, 0xffff0000, v186
	v_pk_mul_f32 v[180:181], v[180:181], v[188:189]
	v_lshlrev_b32_e32 v188, 16, v187
	v_and_b32_e32 v189, 0xffff0000, v187
	v_pk_mul_f32 v[182:183], v[182:183], v[188:189]
	v_cvt_pk_bf16_f32 v176, v176, v177
	v_cvt_pk_bf16_f32 v177, v178, v179
	v_cvt_pk_bf16_f32 v178, v180, v181
	v_cvt_pk_bf16_f32 v179, v182, v183
	s_nop 1
	v_mfma_f32_16x16x32_bf16 v[136:139], v[100:103], v[176:179], v[112:115]
	s_waitcnt vmcnt(34)
	v_mfma_f32_16x16x32_bf16 v[140:143], v[104:107], v[176:179], v[116:119]
	s_add_i32 s24, s19, -2
	s_add_i32 s21, s26, 3
	s_mov_b64 s[22:23], 0
	v_mov_b32_e32 v100, s20

; __device__ __forceinline__ unsigned pack2(float a, float b) { const f32v2_t v = {a, b}; return __builtin_bit_cast(unsigned, __builtin_convertvector(v, bf16v2_t)); }
; __device__ __forceinline__ f32x4 mfma16(bf16x8 a, bf16x8 b, f32x4 c) { return __builtin_amdgcn_mfma_f32_16x16x32_bf16(a, b, c, 0, 0, 0); }
; __device__ __forceinline__ void ssd_scan_item(CParams& p, int j2, int b, int dir, int h, int pq, bf16_t* smem) {
;     ...
;         lds_sync();
;         *(u32x4*)(sX + (tid >> 4) * SST + (tid & 15) * 8) = S.xq;
; #pragma unroll
;         for (int nt = 0; nt < 2; ++nt) st4bf(sH + l16 * SST + wave * 32 + nt * 16 + quad * 4, st[nt][0], st[nt][1], st[nt][2], st[nt][3]);
;         if (wave < 2) {
;             const f32x2 sc2 = scan128(S.dt0 * a, S.dt1 * a, lane, dir);
;     ...
;         {
;             const float dec = sdec[0];
;             st[0] *= dec; st[1] *= dec;
; #pragma unroll
;             for (int ks = 0; ks < 4; ++ks) {
;                 const f32x4 w0 = *(const f32x4*)(sw + ks * 32 + quad * 8), w1 = *(const f32x4*)(sw + ks * 32 + quad * 8 + 4);
;                 const u32x4 raw = *(const u32x4*)(sX + l16 * SST + ks * 32 + quad * 8);
;                 u32x4 xs;
;                 xs.x = pack2(__uint_as_float(raw.x << 16) * w0[0], __uint_as_float(raw.x & 0xffff0000u) * w0[1]);
;                 xs.y = pack2(__uint_as_float(raw.y << 16) * w0[2], __uint_as_float(raw.y & 0xffff0000u) * w0[3]);
;                 xs.z = pack2(__uint_as_float(raw.z << 16) * w1[0], __uint_as_float(raw.z & 0xffff0000u) * w1[1]);
;                 xs.w = pack2(__uint_as_float(raw.w << 16) * w1[2], __uint_as_float(raw.w & 0xffff0000u) * w1[3]);
;                 const bf16x8 xbf = __builtin_bit_cast(bf16x8, xs);
; #pragma unroll
;                 for (int nt = 0; nt < 2; ++nt) st[nt] = mfma16(__builtin_bit_cast(bf16x8, S.bt[nt][ks]), xbf, st[nt]);
;             }
;         }
;         __builtin_amdgcn_sched_barrier(0);
;         load_bt(S, row2);
.LBB0_482:
	ds_read_b32 v246, v165 offset:9728
	ds_read_b128 v[178:181], v172 offset:9216
	ds_read_b128 v[182:185], v172 offset:9232
	ds_read_b128 v[186:189], v170
	ds_read_b128 v[220:223], v172 offset:9344
	ds_read_b128 v[224:227], v172 offset:9360
	ds_read_b128 v[228:231], v170 offset:64
	s_waitcnt lgkmcnt(6)
	v_pk_mul_f32 v[138:139], v[138:139], v[246:247] op_sel_hi:[1,0]
	v_pk_mul_f32 v[136:137], v[136:137], v[246:247] op_sel_hi:[1,0]
	v_pk_mul_f32 v[142:143], v[142:143], v[246:247] op_sel_hi:[1,0]
	v_pk_mul_f32 v[140:141], v[140:141], v[246:247] op_sel_hi:[1,0]
	s_waitcnt lgkmcnt(3)
	v_lshlrev_b32_e32 v190, 16, v186
	v_and_b32_e32 v191, 0xffff0000, v186
	v_pk_mul_f32 v[178:179], v[178:179], v[190:191]
	v_lshlrev_b32_e32 v190, 16, v187
	v_and_b32_e32 v191, 0xffff0000, v187
	v_pk_mul_f32 v[180:181], v[180:181], v[190:191]
	v_lshlrev_b32_e32 v190, 16, v188
	v_and_b32_e32 v191, 0xffff0000, v188
	v_pk_mul_f32 v[182:183], v[182:183], v[190:191]
	v_lshlrev_b32_e32 v190, 16, v189
	v_and_b32_e32 v191, 0xffff0000, v189
	v_pk_mul_f32 v[184:185], v[184:185], v[190:191]
	v_cvt_pk_bf16_f32 v178, v178, v179
	v_cvt_pk_bf16_f32 v179, v180, v181
	v_cvt_pk_bf16_f32 v180, v182, v183
	v_cvt_pk_bf16_f32 v181, v184, v185
	ds_read_b128 v[232:235], v172 offset:9472
	ds_read_b128 v[236:239], v172 offset:9488
	ds_read_b128 v[240:243], v170 offset:128
	s_waitcnt vmcnt(39)
	s_nop 1
	v_mfma_f32_16x16x32_bf16 v[92:95], v[92:95], v[178:181], v[136:139]
	s_waitcnt vmcnt(35)
	v_mfma_f32_16x16x32_bf16 v[96:99], v[96:99], v[178:181], v[140:143]
	s_waitcnt lgkmcnt(3)
	v_lshlrev_b32_e32 v244, 16, v228
	v_and_b32_e32 v245, 0xffff0000, v228
	v_pk_mul_f32 v[220:221], v[220:221], v[244:245]
	v_lshlrev_b32_e32 v244, 16, v229
	v_and_b32_e32 v245, 0xffff0000, v229
	v_pk_mul_f32 v[222:223], v[222:223], v[244:245]
	v_lshlrev_b32_e32 v244, 16, v230
	v_and_b32_e32 v245, 0xffff0000, v230
	v_pk_mul_f32 v[224:225], v[224:225], v[244:245]
	v_lshlrev_b32_e32 v244, 16, v231
	v_and_b32_e32 v245, 0xffff0000, v231
	v_pk_mul_f32 v[226:227], v[226:227], v[244:245]
	v_cvt_pk_bf16_f32 v220, v220, v221
	v_cvt_pk_bf16_f32 v221, v222, v223
	v_cvt_pk_bf16_f32 v222, v224, v225
	v_cvt_pk_bf16_f32 v223, v226, v227
	ds_read_b128 v[178:181], v172 offset:9600
	ds_read_b128 v[182:185], v172 offset:9616
	ds_read_b128 v[186:189], v170 offset:192
	s_nop 1
	v_mfma_f32_16x16x32_bf16 v[80:83], v[80:83], v[220:223], v[92:95]
	s_waitcnt vmcnt(34)
	v_mfma_f32_16x16x32_bf16 v[84:87], v[84:87], v[220:223], v[96:99]
	s_waitcnt lgkmcnt(3)
	v_lshlrev_b32_e32 v244, 16, v240
	v_and_b32_e32 v245, 0xffff0000, v240
	v_pk_mul_f32 v[232:233], v[232:233], v[244:245]
	v_lshlrev_b32_e32 v244, 16, v241
	v_and_b32_e32 v245, 0xffff0000, v241
	v_pk_mul_f32 v[234:235], v[234:235], v[244:245]
	v_lshlrev_b32_e32 v244, 16, v242
	v_and_b32_e32 v245, 0xffff0000, v242
	v_pk_mul_f32 v[236:237], v[236:237], v[244:245]
	v_lshlrev_b32_e32 v244, 16, v243
	v_and_b32_e32 v245, 0xffff0000, v243
	v_pk_mul_f32 v[238:239], v[238:239], v[244:245]
	v_cvt_pk_bf16_f32 v232, v232, v233
	v_cvt_pk_bf16_f32 v233, v234, v235
	v_cvt_pk_bf16_f32 v234, v236, v237
	v_cvt_pk_bf16_f32 v235, v238, v239
	s_nop 1
	v_mfma_f32_16x16x32_bf16 v[72:75], v[72:75], v[232:235], v[80:83]
	s_waitcnt vmcnt(33)
	v_mfma_f32_16x16x32_bf16 v[76:79], v[76:79], v[232:235], v[84:87]
	s_waitcnt lgkmcnt(0)
	v_lshlrev_b32_e32 v190, 16, v186
	v_and_b32_e32 v191, 0xffff0000, v186
	v_pk_mul_f32 v[178:179], v[178:179], v[190:191]
	v_lshlrev_b32_e32 v190, 16, v187
	v_and_b32_e32 v191, 0xffff0000, v187
	v_pk_mul_f32 v[180:181], v[180:181], v[190:191]
	v_lshlrev_b32_e32 v190, 16, v188
	v_and_b32_e32 v191, 0xffff0000, v188
	v_pk_mul_f32 v[182:183], v[182:183], v[190:191]
	v_lshlrev_b32_e32 v190, 16, v189
	v_and_b32_e32 v191, 0xffff0000, v189
	v_pk_mul_f32 v[184:185], v[184:185], v[190:191]
	v_cvt_pk_bf16_f32 v178, v178, v179
	v_cvt_pk_bf16_f32 v179, v180, v181
	v_cvt_pk_bf16_f32 v180, v182, v183
	v_cvt_pk_bf16_f32 v181, v184, v185
	s_nop 1
	v_mfma_f32_16x16x32_bf16 v[140:143], v[32:35], v[178:181], v[72:75]
	s_waitcnt vmcnt(32)
	v_mfma_f32_16x16x32_bf16 v[136:139], v[36:39], v[178:181], v[76:79]
	s_ashr_i32 s22, s22, 5
	s_ashr_i32 s23, s22, 31
	s_lshl_b64 s[22:23], s[22:23], 10
	v_lshl_add_u64 v[36:37], v[154:155], 0, s[22:23]
	global_load_dwordx4 v[92:95], v[36:37], off
	global_load_dwordx4 v[80:83], v[36:37], off offset:1024
	global_load_dwordx4 v[72:75], v[36:37], off offset:2048
	global_load_dwordx4 v[32:35], v[36:37], off offset:3072
	v_add_co_u32_e32 v36, vcc, s36, v36
	s_nop 1
	v_addc_co_u32_e32 v37, vcc, 0, v37, vcc
	global_load_dwordx4 v[96:99], v[36:37], off
	global_load_dwordx4 v[84:87], v[36:37], off offset:1024
	global_load_dwordx4 v[76:79], v[36:37], off offset:2048
	s_nop 0
	global_load_dwordx4 v[36:39], v[36:37], off offset:3072
	s_barrier
	s_waitcnt vmcnt(39)
	ds_write_b128 v164, v[108:111]
	v_cvt_pk_bf16_f32 v108, v140, v141
	v_cvt_pk_bf16_f32 v109, v142, v143
	v_cvt_pk_bf16_f32 v110, v136, v137
	v_cvt_pk_bf16_f32 v111, v138, v139
	ds_write2_b64 v176, v[108:109], v[110:111] offset0:32 offset1:36
	s_and_saveexec_b64 s[22:23], s[44:45]
	s_cbranch_execz .LBB0_496
	s_waitcnt vmcnt(38)
	v_mul_f32_e64 v110, v173, -v163
	s_waitcnt vmcnt(37)
	v_mul_f32_e64 v109, v175, -v163
	s_and_b64 vcc, exec, s[70:71]
	v_mov_b32_e32 v111, v110
	v_mov_b32_e32 v178, v109
	s_cbranch_vccz .Lsc1_bwd
	v_add_f32_dpp v111, v110, v111 row_shr:1 row_mask:0xf bank_mask:0xf bound_ctrl:0
	v_add_f32_dpp v178, v109, v178 row_shr:1 row_mask:0xf bank_mask:0xf bound_ctrl:0
	v_add_f32_dpp v111, v110, v111 row_shr:2 row_mask:0xf bank_mask:0xf bound_ctrl:0
	v_add_f32_dpp v178, v109, v178 row_shr:2 row_mask:0xf bank_mask:0xf bound_ctrl:0
	v_add_f32_dpp v111, v110, v111 row_shr:3 row_mask:0xf bank_mask:0xf bound_ctrl:0
	v_add_f32_dpp v178, v109, v178 row_shr:3 row_mask:0xf bank_mask:0xf bound_ctrl:0
	s_nop 1
	v_add_f32_dpp v111, v111, v111 row_shr:4 row_mask:0xf bank_mask:0xe
	v_add_f32_dpp v178, v178, v178 row_shr:4 row_mask:0xf bank_mask:0xe
	s_nop 1
	v_add_f32_dpp v111, v111, v111 row_shr:8 row_mask:0xf bank_mask:0xc
	v_add_f32_dpp v178, v178, v178 row_shr:8 row_mask:0xf bank_mask:0xc
	s_nop 1
	v_add_f32_dpp v111, v111, v111 row_bcast:15 row_mask:0xa bank_mask:0xf
	v_add_f32_dpp v178, v178, v178 row_bcast:15 row_mask:0xa bank_mask:0xf
	s_nop 1
	v_add_f32_dpp v111, v111, v111 row_bcast:31 row_mask:0xc bank_mask:0xf
	v_add_f32_dpp v178, v178, v178 row_bcast:31 row_mask:0xc bank_mask:0xf
	s_nop 1
	v_readlane_b32 s24, v111, 63
	s_nop 3
	v_add_f32_e32 v178, s24, v178
	s_nop 1
	v_readlane_b32 s24, v178, 63
	s_nop 3
	v_mov_b32_e32 v108, s24
	s_branch .Lsc1_join
